# v11 + peeled first K-loop iteration after an epilogue with store-aware waits (vmcnt 24), steady-state loop untouched
# speedup vs baseline: 1.0058x; 1.0040x over previous
; #define PG8_STAGE(bufoff, gbase, voff) do { _Pragma("unroll") for (int _i = 0; _i < 2; ++_i) \
;         __builtin_amdgcn_global_load_lds((const unsigned*)((const char*)(gbase) + (voff)[_i]), (LAS unsigned*)(lds + (bufoff) + ldsw + _i * 8192), 16, 0, 0); } while (0)
; #define PG8_LDA(dst, b, h) do { _Pragma("unroll") for (int m = 0; m < 4; ++m) _Pragma("unroll") for (int k = 0; k < 2; ++k) dst[m][k] = *(const LAS bf16x8*)(lds + PG8_SA(b, h) + aoff + m * 2048 + k * 1024); } while (0)
; #define PG8_LDB(dst, b, h) do { _Pragma("unroll") for (int n = 0; n < 2; ++n) _Pragma("unroll") for (int k = 0; k < 2; ++k) dst[n][k] = *(const LAS bf16x8*)(lds + PG8_SB(b, h) + boff + n * 2048 + k * 1024); } while (0)
; #define PG8_MMA(ai, bj, At, Bt) do { __builtin_amdgcn_s_setprio(1); _Pragma("unroll") for (int m = 0; m < 4; ++m) _Pragma("unroll") for (int n = 0; n < 2; ++n) _Pragma("unroll") for (int k = 0; k < 2; ++k) \
;         acc[ai][bj][m][n] = __builtin_amdgcn_mfma_f32_16x16x32_bf16(Bt[n][k], At[m][k], acc[ai][bj][m][n], 0, 0, 0); __builtin_amdgcn_s_setprio(0); } while (0)
; #define PG8_WAIT_V(n) asm volatile("s_waitcnt vmcnt(" #n ")" ::: "memory")
; #define PG8_WAIT_L(n) asm volatile("s_waitcnt lgkmcnt(" #n ")" ::: "memory")
; #define PG8_BAR __builtin_amdgcn_s_barrier()
; #define PG8_SCHED __builtin_amdgcn_sched_barrier(0)
; __device__ __forceinline__ void gemm_phase(LAS unsigned char* lds, const GemmP g, const EpiP e) {
;     ...
;         for (int t = 0; t < nt; t += 2) {
;             const bool last = (t == nt - 2);
;             const char* a1 = cA + (size_t)(t + 1) * kstepA;
;             const char* a2 = last ? nA : cA + (size_t)(t + 2) * kstepA; const char* b2 = last ? nB : cB + (size_t)(t + 2) * kstepB;
;             const char* a3 = a2 + kstepA; const char* b3 = b2 + kstepB;
;             PG8_LDB(B0, 0, 0); PG8_LDB(B1, 0, 1); PG8_SCHED; PG8_LDA(At, 0, 0); PG8_STAGE(PG8_SA(1, 1), a1 + hstepA, voffA);
;             PG8_WAIT_V(8); PG8_WAIT_L(0); PG8_BAR; PG8_MMA(0, 0, At, B0); PG8_MMA(0, 1, At, B1); PG8_BAR; PG8_SCHED;
;             PG8_LDA(At, 0, 1); PG8_STAGE(PG8_SB(0, 0), b2, voffB); PG8_STAGE(PG8_SB(0, 1), b2 + hstepB, voffB); PG8_STAGE(PG8_SA(0, 0), a2, voffA);
;             PG8_WAIT_V(8); PG8_WAIT_L(0); PG8_BAR; PG8_MMA(1, 0, At, B0); PG8_MMA(1, 1, At, B1); PG8_BAR; PG8_SCHED;
.LBB0_392:
	s_cmp_lt_i32 s69, 1
	s_cbranch_scc1 .LBB0_395
	s_add_u32 s24, s78, s90
	s_addc_u32 s25, s79, s7
	s_add_i32 s26, s69, -2
	s_add_u32 s27, s40, 0x100
	s_addc_u32 s28, s41, 0
	s_mov_b64 s[18:19], 0
	s_cmp_eq_u32 s99, 0
	s_cbranch_scc1 .LBB0_394
	s_mov_b32 s99, 0
	s_add_u32 s30, s18, 1
	s_addc_u32 s31, s19, 0
	s_add_u32 s16, s18, 2
	s_addc_u32 s17, s19, 0
	s_lshl_b64 s[20:21], s[16:17], s77
	s_add_u32 s19, s78, s20
	s_addc_u32 s20, s79, s21
	s_cmp_eq_u32 s26, s18
	s_cselect_b32 s21, s51, s20
	s_cselect_b32 s20, s50, s19
	s_cselect_b32 s22, s80, s27
	s_cselect_b32 s23, s81, s28
	s_add_u32 s18, s20, s38
	s_addc_u32 s19, s21, s39
	s_add_i32 s29, 0, 0x10000
	v_add_u32_e32 v96, s29, v179
	s_add_i32 s34, 0, 0x14000
	ds_read_b128 v[132:135], v96
	ds_read_b128 v[136:139], v96 offset:1024
	ds_read_b128 v[160:163], v96 offset:2048
	ds_read_b128 v[164:167], v96 offset:3072
	v_add_u32_e32 v96, s34, v179
	ds_read_b128 v[168:171], v96
	ds_read_b128 v[172:175], v96 offset:1024
	ds_read_b128 v[216:219], v96 offset:2048
	ds_read_b128 v[220:223], v96 offset:3072
	s_lshl_b64 s[30:31], s[30:31], s77
	s_add_u32 s30, s24, s30
	s_addc_u32 s31, s25, s31
	v_lshl_add_u64 v[98:99], s[30:31], 0, v[140:141]
	s_add_i32 m0, s92, 0xc000
	ds_read_b128 v[224:227], v188
	ds_read_b128 v[228:231], v188 offset:1024
	ds_read_b128 v[232:235], v188 offset:2048
	ds_read_b128 v[236:239], v188 offset:3072
	ds_read_b128 v[240:243], v188 offset:4096
	ds_read_b128 v[244:247], v188 offset:5120
	ds_read_b128 v[248:251], v188 offset:6144
	ds_read_b128 v[204:207], v188 offset:7168
	global_load_lds_dwordx4 v[98:99], off
	v_lshl_add_u64 v[98:99], s[30:31], 0, v[142:143]
	s_add_i32 m0, s92, 0xe000
	s_nop 0
	global_load_lds_dwordx4 v[98:99], off
	s_waitcnt vmcnt(24)
	s_waitcnt lgkmcnt(0)
	s_barrier
	s_setprio 1
	s_waitcnt lgkmcnt(0)
	v_mfma_f32_16x16x32_bf16 v[128:131], v[132:135], v[224:227], v[128:131]
	v_mfma_f32_16x16x32_bf16 v[124:127], v[160:163], v[224:227], v[124:127]
	v_mfma_f32_16x16x32_bf16 v[120:123], v[132:135], v[232:235], v[120:123]
	v_mfma_f32_16x16x32_bf16 v[116:119], v[160:163], v[232:235], v[116:119]
	v_mfma_f32_16x16x32_bf16 v[112:115], v[132:135], v[240:243], v[112:115]
	v_mfma_f32_16x16x32_bf16 v[108:111], v[160:163], v[240:243], v[108:111]
	v_mfma_f32_16x16x32_bf16 v[104:107], v[132:135], v[248:251], v[104:107]
	v_mfma_f32_16x16x32_bf16 v[98:101], v[160:163], v[248:251], v[100:103]
	v_mfma_f32_16x16x32_bf16 v[128:131], v[136:139], v[228:231], v[128:131]
	v_mfma_f32_16x16x32_bf16 v[124:127], v[164:167], v[228:231], v[124:127]
	v_mfma_f32_16x16x32_bf16 v[120:123], v[136:139], v[236:239], v[120:123]
	v_mfma_f32_16x16x32_bf16 v[116:119], v[164:167], v[236:239], v[116:119]
	v_mfma_f32_16x16x32_bf16 v[112:115], v[136:139], v[244:247], v[112:115]
	v_mfma_f32_16x16x32_bf16 v[108:111], v[164:167], v[244:247], v[108:111]
	v_mfma_f32_16x16x32_bf16 v[104:107], v[136:139], v[204:207], v[104:107]
	v_mfma_f32_16x16x32_bf16 v[98:101], v[164:167], v[204:207], v[98:101]
	s_setprio 0
	s_setprio 1
	v_mfma_f32_16x16x32_bf16 v[92:95], v[168:171], v[224:227], v[92:95]
	v_mfma_f32_16x16x32_bf16 v[88:91], v[216:219], v[224:227], v[88:91]
	v_mfma_f32_16x16x32_bf16 v[84:87], v[168:171], v[232:235], v[84:87]
	v_mfma_f32_16x16x32_bf16 v[80:83], v[216:219], v[232:235], v[80:83]
	v_mfma_f32_16x16x32_bf16 v[76:79], v[168:171], v[240:243], v[76:79]
	v_mfma_f32_16x16x32_bf16 v[72:75], v[216:219], v[240:243], v[72:75]
	v_mfma_f32_16x16x32_bf16 v[68:71], v[168:171], v[248:251], v[68:71]
	v_mfma_f32_16x16x32_bf16 v[64:67], v[216:219], v[248:251], v[64:67]
	v_mfma_f32_16x16x32_bf16 v[92:95], v[172:175], v[228:231], v[92:95]
	v_mfma_f32_16x16x32_bf16 v[88:91], v[220:223], v[228:231], v[88:91]
	v_mfma_f32_16x16x32_bf16 v[84:87], v[172:175], v[236:239], v[84:87]
	v_mfma_f32_16x16x32_bf16 v[80:83], v[220:223], v[236:239], v[80:83]
	v_mfma_f32_16x16x32_bf16 v[76:79], v[172:175], v[244:247], v[76:79]
	v_mfma_f32_16x16x32_bf16 v[72:75], v[220:223], v[244:247], v[72:75]
	v_mfma_f32_16x16x32_bf16 v[68:71], v[172:175], v[204:207], v[68:71]
	v_mfma_f32_16x16x32_bf16 v[64:67], v[220:223], v[204:207], v[64:67]
	s_setprio 0
	s_barrier
	s_add_i32 s29, s29, s91
	v_lshl_add_u64 v[176:177], s[22:23], 0, v[146:147]
	s_mov_b32 m0, s29
	ds_read_b128 v[204:207], v188 offset:16384
	ds_read_b128 v[224:227], v188 offset:17408
	ds_read_b128 v[228:231], v188 offset:18432
	ds_read_b128 v[232:235], v188 offset:19456
	ds_read_b128 v[236:239], v188 offset:20480
	ds_read_b128 v[240:243], v188 offset:21504
	ds_read_b128 v[244:247], v188 offset:22528
	ds_read_b128 v[248:251], v188 offset:23552
	global_load_lds_dwordx4 v[176:177], off
	s_add_i32 m0, s29, 0x2000
	v_lshl_add_u64 v[210:211], s[22:23], 0, v[144:145]
	s_add_u32 s22, s22, s48
	s_addc_u32 s23, s23, s49
	s_add_i32 s29, s34, s91
	global_load_lds_dwordx4 v[210:211], off
	v_lshl_add_u64 v[212:213], s[22:23], 0, v[146:147]
	s_mov_b32 m0, s29
	v_lshl_add_u64 v[190:191], s[22:23], 0, v[144:145]
	global_load_lds_dwordx4 v[212:213], off
	s_add_i32 m0, s29, 0x2000
	v_lshl_add_u64 v[102:103], s[20:21], 0, v[140:141]
	global_load_lds_dwordx4 v[190:191], off
	s_mov_b32 m0, s92
	s_nop 0
	global_load_lds_dwordx4 v[102:103], off
	v_lshl_add_u64 v[102:103], s[20:21], 0, v[142:143]
	s_mov_b32 m0, s93
	s_nop 0
	global_load_lds_dwordx4 v[102:103], off
	s_waitcnt vmcnt(24)
	s_waitcnt lgkmcnt(0)
	s_barrier
; #define PG8_STAGE(bufoff, gbase, voff) do { _Pragma("unroll") for (int _i = 0; _i < 2; ++_i) \
;         __builtin_amdgcn_global_load_lds((const unsigned*)((const char*)(gbase) + (voff)[_i]), (LAS unsigned*)(lds + (bufoff) + ldsw + _i * 8192), 16, 0, 0); } while (0)
; #define PG8_LDA(dst, b, h) do { _Pragma("unroll") for (int m = 0; m < 4; ++m) _Pragma("unroll") for (int k = 0; k < 2; ++k) dst[m][k] = *(const LAS bf16x8*)(lds + PG8_SA(b, h) + aoff + m * 2048 + k * 1024); } while (0)
; #define PG8_LDB(dst, b, h) do { _Pragma("unroll") for (int n = 0; n < 2; ++n) _Pragma("unroll") for (int k = 0; k < 2; ++k) dst[n][k] = *(const LAS bf16x8*)(lds + PG8_SB(b, h) + boff + n * 2048 + k * 1024); } while (0)
; #define PG8_MMA(ai, bj, At, Bt) do { __builtin_amdgcn_s_setprio(1); _Pragma("unroll") for (int m = 0; m < 4; ++m) _Pragma("unroll") for (int n = 0; n < 2; ++n) _Pragma("unroll") for (int k = 0; k < 2; ++k) \
;         acc[ai][bj][m][n] = __builtin_amdgcn_mfma_f32_16x16x32_bf16(Bt[n][k], At[m][k], acc[ai][bj][m][n], 0, 0, 0); __builtin_amdgcn_s_setprio(0); } while (0)
; #define PG8_WAIT_V(n) asm volatile("s_waitcnt vmcnt(" #n ")" ::: "memory")
; #define PG8_WAIT_L(n) asm volatile("s_waitcnt lgkmcnt(" #n ")" ::: "memory")
; #define PG8_BAR __builtin_amdgcn_s_barrier()
; #define PG8_SCHED __builtin_amdgcn_sched_barrier(0)
; __device__ __forceinline__ void gemm_phase(LAS unsigned char* lds, const GemmP g, const EpiP e) {
;     ...
;             PG8_WAIT_V(8); PG8_WAIT_L(0); PG8_BAR; PG8_MMA(1, 0, At, B0); PG8_MMA(1, 1, At, B1); PG8_BAR; PG8_SCHED;
;             PG8_LDB(B0, 1, 0); PG8_LDB(B1, 1, 1); PG8_SCHED; PG8_LDA(At, 1, 0); PG8_STAGE(PG8_SA(0, 1), a2 + hstepA, voffA);
;             PG8_WAIT_V(8); PG8_WAIT_L(0); PG8_BAR; PG8_MMA(0, 0, At, B0); PG8_MMA(0, 1, At, B1); PG8_BAR; PG8_SCHED;
	s_setprio 1
	s_waitcnt lgkmcnt(0)
	v_mfma_f32_16x16x32_bf16 v[60:63], v[132:135], v[204:207], v[60:63]
	v_mfma_f32_16x16x32_bf16 v[56:59], v[160:163], v[204:207], v[56:59]
	v_mfma_f32_16x16x32_bf16 v[52:55], v[132:135], v[228:231], v[52:55]
	v_mfma_f32_16x16x32_bf16 v[48:51], v[160:163], v[228:231], v[48:51]
	v_mfma_f32_16x16x32_bf16 v[44:47], v[132:135], v[236:239], v[44:47]
	v_mfma_f32_16x16x32_bf16 v[40:43], v[160:163], v[236:239], v[40:43]
	v_mfma_f32_16x16x32_bf16 v[36:39], v[132:135], v[244:247], v[36:39]
	v_mfma_f32_16x16x32_bf16 v[32:35], v[160:163], v[244:247], v[32:35]
	v_mfma_f32_16x16x32_bf16 v[60:63], v[136:139], v[224:227], v[60:63]
	v_mfma_f32_16x16x32_bf16 v[56:59], v[164:167], v[224:227], v[56:59]
	v_mfma_f32_16x16x32_bf16 v[52:55], v[136:139], v[232:235], v[52:55]
	v_mfma_f32_16x16x32_bf16 v[48:51], v[164:167], v[232:235], v[48:51]
	v_mfma_f32_16x16x32_bf16 v[44:47], v[136:139], v[240:243], v[44:47]
	v_mfma_f32_16x16x32_bf16 v[40:43], v[164:167], v[240:243], v[40:43]
	v_mfma_f32_16x16x32_bf16 v[36:39], v[136:139], v[248:251], v[36:39]
	v_mfma_f32_16x16x32_bf16 v[32:35], v[164:167], v[248:251], v[32:35]
	s_setprio 0
	s_setprio 1
	v_mfma_f32_16x16x32_bf16 v[28:31], v[168:171], v[204:207], v[28:31]
	v_mfma_f32_16x16x32_bf16 v[24:27], v[216:219], v[204:207], v[24:27]
	v_mfma_f32_16x16x32_bf16 v[20:23], v[168:171], v[228:231], v[20:23]
	v_mfma_f32_16x16x32_bf16 v[16:19], v[216:219], v[228:231], v[16:19]
	v_mfma_f32_16x16x32_bf16 v[12:15], v[168:171], v[236:239], v[12:15]
	v_mfma_f32_16x16x32_bf16 v[8:11], v[216:219], v[236:239], v[8:11]
	v_mfma_f32_16x16x32_bf16 v[4:7], v[168:171], v[244:247], v[4:7]
	v_mfma_f32_16x16x32_bf16 v[0:3], v[216:219], v[244:247], v[0:3]
	v_mfma_f32_16x16x32_bf16 v[28:31], v[172:175], v[224:227], v[28:31]
	v_mfma_f32_16x16x32_bf16 v[24:27], v[220:223], v[224:227], v[24:27]
	v_mfma_f32_16x16x32_bf16 v[20:23], v[172:175], v[232:235], v[20:23]
	v_mfma_f32_16x16x32_bf16 v[16:19], v[220:223], v[232:235], v[16:19]
	v_mfma_f32_16x16x32_bf16 v[12:15], v[172:175], v[240:243], v[12:15]
	v_mfma_f32_16x16x32_bf16 v[8:11], v[220:223], v[240:243], v[8:11]
	v_mfma_f32_16x16x32_bf16 v[4:7], v[172:175], v[248:251], v[4:7]
	v_mfma_f32_16x16x32_bf16 v[0:3], v[220:223], v[248:251], v[0:3]
	s_setprio 0
	s_barrier
	s_add_i32 s22, 0, 0x18000
	v_add_u32_e32 v96, s22, v179
	s_add_i32 s23, 0, 0x1c000
	ds_read_b128 v[132:135], v96
	ds_read_b128 v[136:139], v96 offset:1024
	ds_read_b128 v[160:163], v96 offset:2048
	ds_read_b128 v[164:167], v96 offset:3072
	v_add_u32_e32 v96, s23, v179
	ds_read_b128 v[168:171], v96
	ds_read_b128 v[172:175], v96 offset:1024
	ds_read_b128 v[204:207], v96 offset:2048
	ds_read_b128 v[216:219], v96 offset:3072
	s_add_u32 s20, s20, s90
	s_addc_u32 s21, s21, s7
	s_mov_b32 m0, s73
	v_lshl_add_u64 v[102:103], s[20:21], 0, v[140:141]
	ds_read_b128 v[220:223], v188 offset:32768
	ds_read_b128 v[224:227], v188 offset:33792
	ds_read_b128 v[228:231], v188 offset:34816
	ds_read_b128 v[232:235], v188 offset:35840
	ds_read_b128 v[236:239], v188 offset:36864
	ds_read_b128 v[240:243], v188 offset:37888
	ds_read_b128 v[244:247], v188 offset:38912
	ds_read_b128 v[248:251], v188 offset:39936
	global_load_lds_dwordx4 v[102:103], off
	v_lshl_add_u64 v[102:103], s[20:21], 0, v[142:143]
	s_mov_b32 m0, s4
	s_nop 0
	global_load_lds_dwordx4 v[102:103], off
	s_waitcnt vmcnt(8)
	s_waitcnt lgkmcnt(0)
	s_barrier
	s_setprio 1
	s_waitcnt lgkmcnt(0)
	v_mfma_f32_16x16x32_bf16 v[128:131], v[132:135], v[220:223], v[128:131]
	v_mfma_f32_16x16x32_bf16 v[124:127], v[160:163], v[220:223], v[124:127]
	v_mfma_f32_16x16x32_bf16 v[120:123], v[132:135], v[228:231], v[120:123]
	v_mfma_f32_16x16x32_bf16 v[116:119], v[160:163], v[228:231], v[116:119]
	v_mfma_f32_16x16x32_bf16 v[112:115], v[132:135], v[236:239], v[112:115]
	v_mfma_f32_16x16x32_bf16 v[108:111], v[160:163], v[236:239], v[108:111]
	v_mfma_f32_16x16x32_bf16 v[102:105], v[132:135], v[244:247], v[104:107]
	v_mfma_f32_16x16x32_bf16 v[98:101], v[160:163], v[244:247], v[98:101]
	v_mfma_f32_16x16x32_bf16 v[128:131], v[136:139], v[224:227], v[128:131]
	v_mfma_f32_16x16x32_bf16 v[124:127], v[164:167], v[224:227], v[124:127]
	v_mfma_f32_16x16x32_bf16 v[120:123], v[136:139], v[232:235], v[120:123]
	v_mfma_f32_16x16x32_bf16 v[116:119], v[164:167], v[232:235], v[116:119]
	v_mfma_f32_16x16x32_bf16 v[112:115], v[136:139], v[240:243], v[112:115]
	v_mfma_f32_16x16x32_bf16 v[108:111], v[164:167], v[240:243], v[108:111]
	v_mfma_f32_16x16x32_bf16 v[104:107], v[136:139], v[248:251], v[102:105]
	v_mfma_f32_16x16x32_bf16 v[100:103], v[164:167], v[248:251], v[98:101]
	s_setprio 0
	s_setprio 1
	v_mfma_f32_16x16x32_bf16 v[92:95], v[168:171], v[220:223], v[92:95]
	v_mfma_f32_16x16x32_bf16 v[88:91], v[204:207], v[220:223], v[88:91]
	v_mfma_f32_16x16x32_bf16 v[84:87], v[168:171], v[228:231], v[84:87]
	v_mfma_f32_16x16x32_bf16 v[80:83], v[204:207], v[228:231], v[80:83]
	v_mfma_f32_16x16x32_bf16 v[76:79], v[168:171], v[236:239], v[76:79]
	v_mfma_f32_16x16x32_bf16 v[72:75], v[204:207], v[236:239], v[72:75]
	v_mfma_f32_16x16x32_bf16 v[68:71], v[168:171], v[244:247], v[68:71]
	v_mfma_f32_16x16x32_bf16 v[64:67], v[204:207], v[244:247], v[64:67]
	v_mfma_f32_16x16x32_bf16 v[92:95], v[172:175], v[224:227], v[92:95]
	v_mfma_f32_16x16x32_bf16 v[88:91], v[216:219], v[224:227], v[88:91]
	v_mfma_f32_16x16x32_bf16 v[84:87], v[172:175], v[232:235], v[84:87]
	v_mfma_f32_16x16x32_bf16 v[80:83], v[216:219], v[232:235], v[80:83]
	v_mfma_f32_16x16x32_bf16 v[76:79], v[172:175], v[240:243], v[76:79]
	v_mfma_f32_16x16x32_bf16 v[72:75], v[216:219], v[240:243], v[72:75]
	v_mfma_f32_16x16x32_bf16 v[68:71], v[172:175], v[248:251], v[68:71]
	v_mfma_f32_16x16x32_bf16 v[64:67], v[216:219], v[248:251], v[64:67]
	s_setprio 0
	s_barrier
; #define PG8_STAGE(bufoff, gbase, voff) do { _Pragma("unroll") for (int _i = 0; _i < 2; ++_i) \
;         __builtin_amdgcn_global_load_lds((const unsigned*)((const char*)(gbase) + (voff)[_i]), (LAS unsigned*)(lds + (bufoff) + ldsw + _i * 8192), 16, 0, 0); } while (0)
; #define PG8_LDA(dst, b, h) do { _Pragma("unroll") for (int m = 0; m < 4; ++m) _Pragma("unroll") for (int k = 0; k < 2; ++k) dst[m][k] = *(const LAS bf16x8*)(lds + PG8_SA(b, h) + aoff + m * 2048 + k * 1024); } while (0)
; #define PG8_MMA(ai, bj, At, Bt) do { __builtin_amdgcn_s_setprio(1); _Pragma("unroll") for (int m = 0; m < 4; ++m) _Pragma("unroll") for (int n = 0; n < 2; ++n) _Pragma("unroll") for (int k = 0; k < 2; ++k) \
;         acc[ai][bj][m][n] = __builtin_amdgcn_mfma_f32_16x16x32_bf16(Bt[n][k], At[m][k], acc[ai][bj][m][n], 0, 0, 0); __builtin_amdgcn_s_setprio(0); } while (0)
; #define PG8_WAIT_V(n) asm volatile("s_waitcnt vmcnt(" #n ")" ::: "memory")
; #define PG8_WAIT_L(n) asm volatile("s_waitcnt lgkmcnt(" #n ")" ::: "memory")
; #define PG8_BAR __builtin_amdgcn_s_barrier()
; #define PG8_SCHED __builtin_amdgcn_sched_barrier(0)
; __device__ __forceinline__ void gemm_phase(LAS unsigned char* lds, const GemmP g, const EpiP e) {
;     ...
;             PG8_LDA(At, 1, 1); PG8_STAGE(PG8_SB(1, 0), b3, voffB); PG8_STAGE(PG8_SB(1, 1), b3 + hstepB, voffB); PG8_STAGE(PG8_SA(1, 0), a3, voffA);
;             PG8_WAIT_V(8); PG8_WAIT_L(0); PG8_BAR; PG8_MMA(1, 0, At, B0); PG8_MMA(1, 1, At, B1); PG8_BAR; PG8_SCHED;
;         }
	s_add_i32 s20, s22, s91
	v_lshl_add_u64 v[98:99], v[176:177], 0, s[96:97]
	s_mov_b32 m0, s20
	ds_read_b128 v[220:223], v188 offset:49152
	ds_read_b128 v[224:227], v188 offset:50176
	ds_read_b128 v[228:231], v188 offset:51200
	ds_read_b128 v[232:235], v188 offset:52224
	ds_read_b128 v[236:239], v188 offset:53248
	ds_read_b128 v[240:243], v188 offset:54272
	ds_read_b128 v[244:247], v188 offset:55296
	ds_read_b128 v[248:251], v188 offset:56320
	global_load_lds_dwordx4 v[98:99], off
	v_lshl_add_u64 v[98:99], v[210:211], 0, s[96:97]
	s_add_i32 m0, s20, 0x2000
	s_add_i32 s20, s23, s91
	global_load_lds_dwordx4 v[98:99], off
	v_lshl_add_u64 v[98:99], v[212:213], 0, s[96:97]
	s_mov_b32 m0, s20
	s_nop 0
	global_load_lds_dwordx4 v[98:99], off
	v_lshl_add_u64 v[98:99], v[190:191], 0, s[96:97]
	s_add_i32 m0, s20, 0x2000
	s_nop 0
	global_load_lds_dwordx4 v[98:99], off
	v_lshl_add_u64 v[98:99], s[18:19], 0, v[140:141]
	s_mov_b32 m0, s5
	s_nop 0
	global_load_lds_dwordx4 v[98:99], off
	v_lshl_add_u64 v[98:99], s[18:19], 0, v[142:143]
	s_mov_b32 m0, s44
	s_nop 0
	global_load_lds_dwordx4 v[98:99], off
	s_waitcnt vmcnt(8)
	s_waitcnt lgkmcnt(0)
	s_barrier
	s_setprio 1
	s_waitcnt lgkmcnt(0)
	v_mfma_f32_16x16x32_bf16 v[60:63], v[132:135], v[220:223], v[60:63]
	v_mfma_f32_16x16x32_bf16 v[56:59], v[160:163], v[220:223], v[56:59]
	v_mfma_f32_16x16x32_bf16 v[52:55], v[132:135], v[228:231], v[52:55]
	v_mfma_f32_16x16x32_bf16 v[48:51], v[160:163], v[228:231], v[48:51]
	v_mfma_f32_16x16x32_bf16 v[44:47], v[132:135], v[236:239], v[44:47]
	v_mfma_f32_16x16x32_bf16 v[40:43], v[160:163], v[236:239], v[40:43]
	v_mfma_f32_16x16x32_bf16 v[36:39], v[132:135], v[244:247], v[36:39]
	v_mfma_f32_16x16x32_bf16 v[32:35], v[160:163], v[244:247], v[32:35]
	v_mfma_f32_16x16x32_bf16 v[60:63], v[136:139], v[224:227], v[60:63]
	v_mfma_f32_16x16x32_bf16 v[56:59], v[164:167], v[224:227], v[56:59]
	v_mfma_f32_16x16x32_bf16 v[52:55], v[136:139], v[232:235], v[52:55]
	v_mfma_f32_16x16x32_bf16 v[48:51], v[164:167], v[232:235], v[48:51]
	v_mfma_f32_16x16x32_bf16 v[44:47], v[136:139], v[240:243], v[44:47]
	v_mfma_f32_16x16x32_bf16 v[40:43], v[164:167], v[240:243], v[40:43]
	v_mfma_f32_16x16x32_bf16 v[36:39], v[136:139], v[248:251], v[36:39]
	v_mfma_f32_16x16x32_bf16 v[32:35], v[164:167], v[248:251], v[32:35]
	s_setprio 0
	s_setprio 1
	v_mfma_f32_16x16x32_bf16 v[28:31], v[168:171], v[220:223], v[28:31]
	v_mfma_f32_16x16x32_bf16 v[24:27], v[204:207], v[220:223], v[24:27]
	v_mfma_f32_16x16x32_bf16 v[20:23], v[168:171], v[228:231], v[20:23]
	v_mfma_f32_16x16x32_bf16 v[16:19], v[204:207], v[228:231], v[16:19]
	v_mfma_f32_16x16x32_bf16 v[12:15], v[168:171], v[236:239], v[12:15]
	v_mfma_f32_16x16x32_bf16 v[8:11], v[204:207], v[236:239], v[8:11]
	v_mfma_f32_16x16x32_bf16 v[4:7], v[168:171], v[244:247], v[4:7]
	v_mfma_f32_16x16x32_bf16 v[0:3], v[204:207], v[244:247], v[0:3]
	v_mfma_f32_16x16x32_bf16 v[28:31], v[172:175], v[224:227], v[28:31]
	v_mfma_f32_16x16x32_bf16 v[24:27], v[216:219], v[224:227], v[24:27]
	v_mfma_f32_16x16x32_bf16 v[20:23], v[172:175], v[232:235], v[20:23]
	v_mfma_f32_16x16x32_bf16 v[16:19], v[216:219], v[232:235], v[16:19]
	v_mfma_f32_16x16x32_bf16 v[12:15], v[172:175], v[240:243], v[12:15]
	v_mfma_f32_16x16x32_bf16 v[8:11], v[216:219], v[240:243], v[8:11]
	v_mfma_f32_16x16x32_bf16 v[4:7], v[172:175], v[248:251], v[4:7]
	v_mfma_f32_16x16x32_bf16 v[0:3], v[216:219], v[248:251], v[0:3]
	s_setprio 0
	s_barrier
	s_add_u32 s27, s27, 0x100
	s_addc_u32 s28, s28, 0
	s_cmp_ge_i32 s16, s69
	s_mov_b64 s[18:19], s[16:17]
	s_cbranch_scc0 .LBB0_394
	s_branch .LBB0_395
